# v25 + first K-loop pass of every P1/P7 unit peeled with inline-0 C operands: no accumulator clears between a unit's epilogue and its K-loop
# speedup vs baseline: 1.0055x; 1.0001x over previous
; #define PG8_STAGE(bufoff, gbase, voff) do { _Pragma("unroll") for (int _i = 0; _i < 2; ++_i) \
;         __builtin_amdgcn_global_load_lds((const unsigned*)((const char*)(gbase) + (voff)[_i]), (PG8_LAS unsigned*)(lds + (bufoff) + ldsw + _i * 8192), 16, 0, 0); } while (0)
; #define PG8_LDA(dst, b, h) do { _Pragma("unroll") for (int m = 0; m < 4; ++m) _Pragma("unroll") for (int k = 0; k < 2; ++k) dst[m][k] = *(const PG8_LAS bf16x8*)(lds + PG8_SA(b, h) + aoff + m * 2048 + k * 1024); } while (0)
; #define PG8_LDB(dst, b, h) do { _Pragma("unroll") for (int n = 0; n < 2; ++n) _Pragma("unroll") for (int k = 0; k < 2; ++k) dst[n][k] = *(const PG8_LAS bf16x8*)(lds + PG8_SB(b, h) + boff + n * 2048 + k * 1024); } while (0)
; #define PG8_WAIT_V(n) asm volatile("s_waitcnt vmcnt(" #n ")" ::: "memory")
; #define PG8_WAIT_L(n) asm volatile("s_waitcnt lgkmcnt(" #n ")" ::: "memory")
; #define PG8_BAR __builtin_amdgcn_s_barrier()
; #define PG8_SCHED __builtin_amdgcn_sched_barrier(0)
; template <class Epi, class Sched, bool ALIGN_EPI = false, bool SP2 = false>
; __device__ __forceinline__ void gemm_phase(PG8_LAS unsigned char* lds, const Gemm g, const Sched& S, const Epi& E) {
;     ...
;         const bool has_next = S.next(ui + 1, nxt);
;         const char* nA = has_next ? (const char*)g.A + (size_t)nxt.pm * tstep : cA; const char* nB = has_next ? (const char*)g.Bt + (size_t)nxt.pn * tstep : cB;
;         for (int t = 0; t < nt; t += 2) {
;             if constexpr (Epi::HAS_MID) { if (t == nt / 2) E.mid(acc, cur, wr, wc, fr, fq); }
;             const bool last = (t == nt - 2);
;             const char* a1 = cA + (size_t)(t + 1) * kstep;
;             const char* a2 = last ? nA : cA + (size_t)(t + 2) * kstep; const char* b2 = last ? nB : cB + (size_t)(t + 2) * kstep;
;             const char* a3 = a2 + kstep; const char* b3 = b2 + kstep;
;             if (last && has_next) S.a_ready(nxt);
;             if constexpr (SP2) {
;             PG8_LDB(B0, 0, 0); PG8_LDB(B1, 0, 1); PG8_SCHED; PG8_LDA(At, 0, 0); PG8_STAGE(PG8_SA(1, 1), a1 + hstep, voffA);
;             PG8_WAIT_V(8); PG8_WAIT_L(0); PG8_BAR; PG8_MMA(0, 0, At, B0); PG8_MMA(0, 1, At, B1); PG8_BAR; PG8_SCHED;
;             PG8_LDA(At, 0, 1); PG8_STAGE(PG8_SB(0, 0), b2, voffB); PG8_STAGE(PG8_SB(0, 1), b2 + hstepB, voffB); PG8_STAGE(PG8_SA(0, 0), a2, voffA);
.LBB0_191:
	s_ashr_i32 s13, s12, 31
	s_lshl_b64 s[14:15], s[12:13], 19
	v_readlane_b32 s16, v241, 53
	v_readlane_b32 s17, v241, 54
	s_add_u32 s14, s16, s14
	s_addc_u32 s15, s17, s15
	s_and_b64 s[16:17], s[2:3], exec
	s_cselect_b32 s5, s15, s21
	s_cselect_b32 s13, s14, s20
	s_ashr_i32 s11, s10, 31
	s_lshl_b64 s[16:17], s[10:11], 19
	v_readlane_b32 s24, v241, 36
	v_readlane_b32 s25, v241, 37
	s_add_u32 s16, s24, s16
	s_addc_u32 s17, s25, s17
	s_and_b64 s[24:25], s[2:3], exec
	s_cselect_b32 s11, s17, s23
	s_cselect_b32 s19, s16, s22
	s_add_u32 s20, s20, 0x40080
	s_addc_u32 s21, s21, 0
	s_add_u32 s73, s22, 0x100
	s_addc_u32 s74, s23, 0
	s_mov_b32 s75, -2
	ds_read_b128 v[146:149], v152
	ds_read_b128 v[156:159], v152 offset:1024
	ds_read_b128 v[160:163], v152 offset:2048
	ds_read_b128 v[164:167], v152 offset:3072
	ds_read_b128 v[168:171], v153
	ds_read_b128 v[172:175], v153 offset:1024
	ds_read_b128 v[176:179], v153 offset:2048
	ds_read_b128 v[180:183], v153 offset:3072
	s_add_u32 s22, s20, 0xfffc0080
	s_addc_u32 s23, s21, -1
	s_cmp_eq_u32 s75, 12
	s_cselect_b32 s25, s5, s23
	s_cselect_b32 s24, s13, s22
	s_cselect_b32 s23, s11, s74
	s_cselect_b32 s22, s19, s73
	v_lshl_add_u64 v[216:217], s[20:21], 0, v[138:139]
	s_add_i32 m0, s27, 0xc000
	ds_read_b128 v[184:187], v154
	ds_read_b128 v[188:191], v154 offset:1024
	ds_read_b128 v[192:195], v154 offset:2048
	ds_read_b128 v[196:199], v154 offset:3072
	ds_read_b128 v[200:203], v154 offset:4096
	ds_read_b128 v[204:207], v154 offset:5120
	ds_read_b128 v[208:211], v154 offset:6144
	ds_read_b128 v[212:215], v154 offset:7168
	global_load_lds_dwordx4 v[216:217], off
	v_lshl_add_u64 v[216:217], s[20:21], 0, v[140:141]
	s_add_i32 m0, s27, 0xe000
	s_nop 0
	global_load_lds_dwordx4 v[216:217], off
	s_waitcnt vmcnt(8)
	s_waitcnt lgkmcnt(0)
	s_barrier
	v_mfma_f32_16x16x32_bf16 v[126:129], v[146:149], v[184:187], 0
	v_mfma_f32_16x16x32_bf16 v[122:125], v[160:163], v[184:187], 0
	v_mfma_f32_16x16x32_bf16 v[114:117], v[146:149], v[192:195], 0
	v_mfma_f32_16x16x32_bf16 v[106:109], v[160:163], v[192:195], 0
	v_mfma_f32_16x16x32_bf16 v[98:101], v[146:149], v[200:203], 0
	v_mfma_f32_16x16x32_bf16 v[90:93], v[160:163], v[200:203], 0
	v_mfma_f32_16x16x32_bf16 v[82:85], v[146:149], v[208:211], 0
	v_mfma_f32_16x16x32_bf16 v[74:77], v[160:163], v[208:211], 0
	v_mfma_f32_16x16x32_bf16 v[126:129], v[156:159], v[188:191], v[126:129]
	v_mfma_f32_16x16x32_bf16 v[122:125], v[164:167], v[188:191], v[122:125]
	v_mfma_f32_16x16x32_bf16 v[114:117], v[156:159], v[196:199], v[114:117]
	v_mfma_f32_16x16x32_bf16 v[106:109], v[164:167], v[196:199], v[106:109]
	v_mfma_f32_16x16x32_bf16 v[98:101], v[156:159], v[204:207], v[98:101]
	v_mfma_f32_16x16x32_bf16 v[90:93], v[164:167], v[204:207], v[90:93]
	v_mfma_f32_16x16x32_bf16 v[82:85], v[156:159], v[212:215], v[82:85]
	v_mfma_f32_16x16x32_bf16 v[74:77], v[164:167], v[212:215], v[74:77]
	v_mfma_f32_16x16x32_bf16 v[118:121], v[168:171], v[184:187], 0
	v_mfma_f32_16x16x32_bf16 v[110:113], v[176:179], v[184:187], 0
	v_mfma_f32_16x16x32_bf16 v[102:105], v[168:171], v[192:195], 0
	v_mfma_f32_16x16x32_bf16 v[94:97], v[176:179], v[192:195], 0
	v_mfma_f32_16x16x32_bf16 v[86:89], v[168:171], v[200:203], 0
	v_mfma_f32_16x16x32_bf16 v[78:81], v[176:179], v[200:203], 0
	v_mfma_f32_16x16x32_bf16 v[70:73], v[168:171], v[208:211], 0
	v_mfma_f32_16x16x32_bf16 v[66:69], v[176:179], v[208:211], 0
	v_mfma_f32_16x16x32_bf16 v[118:121], v[172:175], v[188:191], v[118:121]
	v_mfma_f32_16x16x32_bf16 v[110:113], v[180:183], v[188:191], v[110:113]
	v_mfma_f32_16x16x32_bf16 v[102:105], v[172:175], v[196:199], v[102:105]
	v_mfma_f32_16x16x32_bf16 v[94:97], v[180:183], v[196:199], v[94:97]
	v_mfma_f32_16x16x32_bf16 v[86:89], v[172:175], v[204:207], v[86:89]
	v_mfma_f32_16x16x32_bf16 v[78:81], v[180:183], v[204:207], v[78:81]
	v_mfma_f32_16x16x32_bf16 v[70:73], v[172:175], v[212:215], v[70:73]
	v_mfma_f32_16x16x32_bf16 v[66:69], v[180:183], v[212:215], v[66:69]
	s_barrier
	s_add_i32 s76, s69, s26
	v_lshl_add_u64 v[216:217], s[22:23], 0, v[132:133]
	s_mov_b32 m0, s76
	ds_read_b128 v[184:187], v154 offset:16384
	ds_read_b128 v[188:191], v154 offset:17408
	ds_read_b128 v[192:195], v154 offset:18432
	ds_read_b128 v[196:199], v154 offset:19456
	ds_read_b128 v[200:203], v154 offset:20480
	ds_read_b128 v[204:207], v154 offset:21504
	ds_read_b128 v[208:211], v154 offset:22528
	ds_read_b128 v[212:215], v154 offset:23552
	global_load_lds_dwordx4 v[216:217], off
	s_add_i32 m0, s76, 0x2000
	s_add_u32 s76, s22, 0x10000
	v_lshl_add_u64 v[218:219], s[22:23], 0, v[136:137]
	s_addc_u32 s77, s23, 0
	s_add_i32 s78, s70, s26
	global_load_lds_dwordx4 v[218:219], off
	v_lshl_add_u64 v[220:221], s[76:77], 0, v[132:133]
	s_mov_b32 m0, s78
	v_lshl_add_u64 v[222:223], s[24:25], 0, v[134:135]
	global_load_lds_dwordx4 v[220:221], off
	v_lshl_add_u64 v[220:221], s[76:77], 0, v[136:137]
	s_add_i32 m0, s78, 0x2000
	s_nop 0
	global_load_lds_dwordx4 v[220:221], off
	v_lshl_add_u64 v[220:221], s[24:25], 0, v[130:131]
	s_mov_b32 m0, s27
	s_nop 0
	global_load_lds_dwordx4 v[220:221], off
	s_mov_b32 m0, s28
	s_nop 0
	global_load_lds_dwordx4 v[222:223], off
	s_waitcnt vmcnt(8)
	s_waitcnt lgkmcnt(0)
	s_barrier
; #define PG8_STAGE(bufoff, gbase, voff) do { _Pragma("unroll") for (int _i = 0; _i < 2; ++_i) \
;         __builtin_amdgcn_global_load_lds((const unsigned*)((const char*)(gbase) + (voff)[_i]), (PG8_LAS unsigned*)(lds + (bufoff) + ldsw + _i * 8192), 16, 0, 0); } while (0)
; #define PG8_LDA(dst, b, h) do { _Pragma("unroll") for (int m = 0; m < 4; ++m) _Pragma("unroll") for (int k = 0; k < 2; ++k) dst[m][k] = *(const PG8_LAS bf16x8*)(lds + PG8_SA(b, h) + aoff + m * 2048 + k * 1024); } while (0)
; #define PG8_LDB(dst, b, h) do { _Pragma("unroll") for (int n = 0; n < 2; ++n) _Pragma("unroll") for (int k = 0; k < 2; ++k) dst[n][k] = *(const PG8_LAS bf16x8*)(lds + PG8_SB(b, h) + boff + n * 2048 + k * 1024); } while (0)
; #define PG8_MMA(ai, bj, At, Bt) do { __builtin_amdgcn_s_setprio(1); _Pragma("unroll") for (int m = 0; m < 4; ++m) _Pragma("unroll") for (int n = 0; n < 2; ++n) _Pragma("unroll") for (int k = 0; k < 2; ++k) \
;         acc[ai][bj][m][n] = __builtin_amdgcn_mfma_f32_16x16x32_bf16(Bt[n][k], At[m][k], acc[ai][bj][m][n], 0, 0, 0); __builtin_amdgcn_s_setprio(0); } while (0)
; #define PG8_WAIT_V(n) asm volatile("s_waitcnt vmcnt(" #n ")" ::: "memory")
; #define PG8_WAIT_L(n) asm volatile("s_waitcnt lgkmcnt(" #n ")" ::: "memory")
; #define PG8_BAR __builtin_amdgcn_s_barrier()
; #define PG8_SCHED __builtin_amdgcn_sched_barrier(0)
; template <class Epi, class Sched, bool ALIGN_EPI = false, bool SP2 = false>
; __device__ __forceinline__ void gemm_phase(PG8_LAS unsigned char* lds, const Gemm g, const Sched& S, const Epi& E) {
;     ...
;             PG8_WAIT_V(8); PG8_WAIT_L(0); PG8_BAR; PG8_MMA(1, 0, At, B0); PG8_MMA(1, 1, At, B1); PG8_BAR; PG8_SCHED;
;             PG8_LDB(B0, 1, 0); PG8_LDB(B1, 1, 1); PG8_SCHED; PG8_LDA(At, 1, 0); PG8_STAGE(PG8_SA(0, 1), a2 + hstep, voffA);
;             PG8_WAIT_V(8); PG8_WAIT_L(0); PG8_BAR; PG8_MMA(0, 0, At, B0); PG8_MMA(0, 1, At, B1); PG8_BAR; PG8_SCHED;
	v_mfma_f32_16x16x32_bf16 v[62:65], v[146:149], v[184:187], 0
	v_mfma_f32_16x16x32_bf16 v[58:61], v[160:163], v[184:187], 0
	v_mfma_f32_16x16x32_bf16 v[50:53], v[146:149], v[192:195], 0
	v_mfma_f32_16x16x32_bf16 v[42:45], v[160:163], v[192:195], 0
	v_mfma_f32_16x16x32_bf16 v[34:37], v[146:149], v[200:203], 0
	v_mfma_f32_16x16x32_bf16 v[26:29], v[160:163], v[200:203], 0
	v_mfma_f32_16x16x32_bf16 v[18:21], v[146:149], v[208:211], 0
	v_mfma_f32_16x16x32_bf16 v[10:13], v[160:163], v[208:211], 0
	v_mfma_f32_16x16x32_bf16 v[62:65], v[156:159], v[188:191], v[62:65]
	v_mfma_f32_16x16x32_bf16 v[58:61], v[164:167], v[188:191], v[58:61]
	v_mfma_f32_16x16x32_bf16 v[50:53], v[156:159], v[196:199], v[50:53]
	v_mfma_f32_16x16x32_bf16 v[42:45], v[164:167], v[196:199], v[42:45]
	v_mfma_f32_16x16x32_bf16 v[34:37], v[156:159], v[204:207], v[34:37]
	v_mfma_f32_16x16x32_bf16 v[26:29], v[164:167], v[204:207], v[26:29]
	v_mfma_f32_16x16x32_bf16 v[18:21], v[156:159], v[212:215], v[18:21]
	v_mfma_f32_16x16x32_bf16 v[10:13], v[164:167], v[212:215], v[10:13]
	v_mfma_f32_16x16x32_bf16 v[54:57], v[168:171], v[184:187], 0
	v_mfma_f32_16x16x32_bf16 v[46:49], v[176:179], v[184:187], 0
	v_mfma_f32_16x16x32_bf16 v[38:41], v[168:171], v[192:195], 0
	v_mfma_f32_16x16x32_bf16 v[30:33], v[176:179], v[192:195], 0
	v_mfma_f32_16x16x32_bf16 v[22:25], v[168:171], v[200:203], 0
	v_mfma_f32_16x16x32_bf16 v[14:17], v[176:179], v[200:203], 0
	v_mfma_f32_16x16x32_bf16 v[6:9], v[168:171], v[208:211], 0
	v_mfma_f32_16x16x32_bf16 v[2:5], v[176:179], v[208:211], 0
	v_mfma_f32_16x16x32_bf16 v[54:57], v[172:175], v[188:191], v[54:57]
	v_mfma_f32_16x16x32_bf16 v[46:49], v[180:183], v[188:191], v[46:49]
	v_mfma_f32_16x16x32_bf16 v[38:41], v[172:175], v[196:199], v[38:41]
	v_mfma_f32_16x16x32_bf16 v[30:33], v[180:183], v[196:199], v[30:33]
	v_mfma_f32_16x16x32_bf16 v[22:25], v[172:175], v[204:207], v[22:25]
	v_mfma_f32_16x16x32_bf16 v[14:17], v[180:183], v[204:207], v[14:17]
	v_mfma_f32_16x16x32_bf16 v[6:9], v[172:175], v[212:215], v[6:9]
	v_mfma_f32_16x16x32_bf16 v[2:5], v[180:183], v[212:215], v[2:5]
	s_barrier
	s_add_i32 s76, 0, 0x18000
	v_add_u32_e32 v155, s76, v150
	s_add_i32 s77, 0, 0x1c000
	ds_read_b128 v[146:149], v155
	ds_read_b128 v[156:159], v155 offset:1024
	ds_read_b128 v[160:163], v155 offset:2048
	ds_read_b128 v[164:167], v155 offset:3072
	v_add_u32_e32 v155, s77, v150
	ds_read_b128 v[168:171], v155
	ds_read_b128 v[172:175], v155 offset:1024
	ds_read_b128 v[176:179], v155 offset:2048
	ds_read_b128 v[180:183], v155 offset:3072
	s_add_u32 s24, s24, 0x40000
	s_addc_u32 s25, s25, 0
	s_mov_b32 m0, s29
	v_lshl_add_u64 v[224:225], s[24:25], 0, v[130:131]
	ds_read_b128 v[184:187], v154 offset:32768
	ds_read_b128 v[188:191], v154 offset:33792
	ds_read_b128 v[192:195], v154 offset:34816
	ds_read_b128 v[196:199], v154 offset:35840
	ds_read_b128 v[200:203], v154 offset:36864
	ds_read_b128 v[204:207], v154 offset:37888
	ds_read_b128 v[208:211], v154 offset:38912
	ds_read_b128 v[212:215], v154 offset:39936
	global_load_lds_dwordx4 v[224:225], off
	v_lshl_add_u64 v[224:225], s[24:25], 0, v[134:135]
	s_mov_b32 m0, s30
	s_nop 0
	global_load_lds_dwordx4 v[224:225], off
	s_waitcnt vmcnt(8)
	s_waitcnt lgkmcnt(0)
	s_barrier
	v_mfma_f32_16x16x32_bf16 v[126:129], v[146:149], v[184:187], v[126:129]
	v_mfma_f32_16x16x32_bf16 v[122:125], v[160:163], v[184:187], v[122:125]
	v_mfma_f32_16x16x32_bf16 v[114:117], v[146:149], v[192:195], v[114:117]
	v_mfma_f32_16x16x32_bf16 v[106:109], v[160:163], v[192:195], v[106:109]
	v_mfma_f32_16x16x32_bf16 v[98:101], v[146:149], v[200:203], v[98:101]
	v_mfma_f32_16x16x32_bf16 v[90:93], v[160:163], v[200:203], v[90:93]
	v_mfma_f32_16x16x32_bf16 v[82:85], v[146:149], v[208:211], v[82:85]
	v_mfma_f32_16x16x32_bf16 v[74:77], v[160:163], v[208:211], v[74:77]
	v_mfma_f32_16x16x32_bf16 v[126:129], v[156:159], v[188:191], v[126:129]
	v_mfma_f32_16x16x32_bf16 v[122:125], v[164:167], v[188:191], v[122:125]
	v_mfma_f32_16x16x32_bf16 v[114:117], v[156:159], v[196:199], v[114:117]
	v_mfma_f32_16x16x32_bf16 v[106:109], v[164:167], v[196:199], v[106:109]
	v_mfma_f32_16x16x32_bf16 v[98:101], v[156:159], v[204:207], v[98:101]
	v_mfma_f32_16x16x32_bf16 v[90:93], v[164:167], v[204:207], v[90:93]
	v_mfma_f32_16x16x32_bf16 v[82:85], v[156:159], v[212:215], v[82:85]
	v_mfma_f32_16x16x32_bf16 v[74:77], v[164:167], v[212:215], v[74:77]
	v_mfma_f32_16x16x32_bf16 v[118:121], v[168:171], v[184:187], v[118:121]
	v_mfma_f32_16x16x32_bf16 v[110:113], v[176:179], v[184:187], v[110:113]
	v_mfma_f32_16x16x32_bf16 v[102:105], v[168:171], v[192:195], v[102:105]
	v_mfma_f32_16x16x32_bf16 v[94:97], v[176:179], v[192:195], v[94:97]
	v_mfma_f32_16x16x32_bf16 v[86:89], v[168:171], v[200:203], v[86:89]
	v_mfma_f32_16x16x32_bf16 v[78:81], v[176:179], v[200:203], v[78:81]
	v_mfma_f32_16x16x32_bf16 v[70:73], v[168:171], v[208:211], v[70:73]
	v_mfma_f32_16x16x32_bf16 v[66:69], v[176:179], v[208:211], v[66:69]
	v_mfma_f32_16x16x32_bf16 v[118:121], v[172:175], v[188:191], v[118:121]
	v_mfma_f32_16x16x32_bf16 v[110:113], v[180:183], v[188:191], v[110:113]
	v_mfma_f32_16x16x32_bf16 v[102:105], v[172:175], v[196:199], v[102:105]
	v_mfma_f32_16x16x32_bf16 v[94:97], v[180:183], v[196:199], v[94:97]
	v_mfma_f32_16x16x32_bf16 v[86:89], v[172:175], v[204:207], v[86:89]
	v_mfma_f32_16x16x32_bf16 v[78:81], v[180:183], v[204:207], v[78:81]
	v_mfma_f32_16x16x32_bf16 v[70:73], v[172:175], v[212:215], v[70:73]
	v_mfma_f32_16x16x32_bf16 v[66:69], v[180:183], v[212:215], v[66:69]
	s_barrier
; #define PG8_STAGE(bufoff, gbase, voff) do { _Pragma("unroll") for (int _i = 0; _i < 2; ++_i) \
;         __builtin_amdgcn_global_load_lds((const unsigned*)((const char*)(gbase) + (voff)[_i]), (PG8_LAS unsigned*)(lds + (bufoff) + ldsw + _i * 8192), 16, 0, 0); } while (0)
; #define PG8_LDA(dst, b, h) do { _Pragma("unroll") for (int m = 0; m < 4; ++m) _Pragma("unroll") for (int k = 0; k < 2; ++k) dst[m][k] = *(const PG8_LAS bf16x8*)(lds + PG8_SA(b, h) + aoff + m * 2048 + k * 1024); } while (0)
; #define PG8_MMA(ai, bj, At, Bt) do { __builtin_amdgcn_s_setprio(1); _Pragma("unroll") for (int m = 0; m < 4; ++m) _Pragma("unroll") for (int n = 0; n < 2; ++n) _Pragma("unroll") for (int k = 0; k < 2; ++k) \
;         acc[ai][bj][m][n] = __builtin_amdgcn_mfma_f32_16x16x32_bf16(Bt[n][k], At[m][k], acc[ai][bj][m][n], 0, 0, 0); __builtin_amdgcn_s_setprio(0); } while (0)
; #define PG8_WAIT_V(n) asm volatile("s_waitcnt vmcnt(" #n ")" ::: "memory")
; #define PG8_WAIT_L(n) asm volatile("s_waitcnt lgkmcnt(" #n ")" ::: "memory")
; #define PG8_BAR __builtin_amdgcn_s_barrier()
; #define PG8_SCHED __builtin_amdgcn_sched_barrier(0)
; template <class Epi, class Sched, bool ALIGN_EPI = false, bool SP2 = false>
; __device__ __forceinline__ void gemm_phase(PG8_LAS unsigned char* lds, const Gemm g, const Sched& S, const Epi& E) {
;     ...
;         for (int t = 0; t < nt; t += 2) {
;     ...
;             PG8_LDA(At, 1, 1); PG8_STAGE(PG8_SB(1, 0), b3, voffB); PG8_STAGE(PG8_SB(1, 1), b3 + hstepB, voffB); PG8_STAGE(PG8_SA(1, 0), a3, voffA);
;             PG8_WAIT_V(8); PG8_WAIT_L(0); PG8_BAR; PG8_MMA(1, 0, At, B0); PG8_MMA(1, 1, At, B1); PG8_BAR; PG8_SCHED;
	s_add_i32 s24, s76, s26
	v_lshl_add_u64 v[216:217], v[216:217], 0, s[6:7]
	s_mov_b32 m0, s24
	ds_read_b128 v[184:187], v154 offset:49152
	ds_read_b128 v[188:191], v154 offset:50176
	ds_read_b128 v[192:195], v154 offset:51200
	ds_read_b128 v[196:199], v154 offset:52224
	ds_read_b128 v[200:203], v154 offset:53248
	ds_read_b128 v[204:207], v154 offset:54272
	ds_read_b128 v[208:211], v154 offset:55296
	ds_read_b128 v[212:215], v154 offset:56320
	global_load_lds_dwordx4 v[216:217], off
	s_add_i32 m0, s24, 0x2000
	s_add_u32 s22, s22, 0x10080
	v_lshl_add_u64 v[216:217], v[218:219], 0, s[6:7]
	s_addc_u32 s23, s23, 0
	s_add_i32 s24, s77, s26
	global_load_lds_dwordx4 v[216:217], off
	v_lshl_add_u64 v[216:217], s[22:23], 0, v[132:133]
	s_mov_b32 m0, s24
	s_nop 0
	global_load_lds_dwordx4 v[216:217], off
	v_lshl_add_u64 v[216:217], s[22:23], 0, v[136:137]
	s_add_i32 m0, s24, 0x2000
	s_nop 0
	global_load_lds_dwordx4 v[216:217], off
	v_lshl_add_u64 v[216:217], v[220:221], 0, s[6:7]
	s_mov_b32 m0, s33
	s_nop 0
	global_load_lds_dwordx4 v[216:217], off
	v_lshl_add_u64 v[216:217], v[222:223], 0, s[6:7]
	s_mov_b32 m0, s34
	s_nop 0
	global_load_lds_dwordx4 v[216:217], off
	s_waitcnt vmcnt(8)
	s_waitcnt lgkmcnt(0)
	s_barrier
	v_mfma_f32_16x16x32_bf16 v[62:65], v[146:149], v[184:187], v[62:65]
	v_mfma_f32_16x16x32_bf16 v[58:61], v[160:163], v[184:187], v[58:61]
	v_mfma_f32_16x16x32_bf16 v[50:53], v[146:149], v[192:195], v[50:53]
	v_mfma_f32_16x16x32_bf16 v[42:45], v[160:163], v[192:195], v[42:45]
	v_mfma_f32_16x16x32_bf16 v[34:37], v[146:149], v[200:203], v[34:37]
	v_mfma_f32_16x16x32_bf16 v[26:29], v[160:163], v[200:203], v[26:29]
	v_mfma_f32_16x16x32_bf16 v[18:21], v[146:149], v[208:211], v[18:21]
	v_mfma_f32_16x16x32_bf16 v[10:13], v[160:163], v[208:211], v[10:13]
	v_mfma_f32_16x16x32_bf16 v[62:65], v[156:159], v[188:191], v[62:65]
	v_mfma_f32_16x16x32_bf16 v[58:61], v[164:167], v[188:191], v[58:61]
	v_mfma_f32_16x16x32_bf16 v[50:53], v[156:159], v[196:199], v[50:53]
	v_mfma_f32_16x16x32_bf16 v[42:45], v[164:167], v[196:199], v[42:45]
	v_mfma_f32_16x16x32_bf16 v[34:37], v[156:159], v[204:207], v[34:37]
	v_mfma_f32_16x16x32_bf16 v[26:29], v[164:167], v[204:207], v[26:29]
	v_mfma_f32_16x16x32_bf16 v[18:21], v[156:159], v[212:215], v[18:21]
	v_mfma_f32_16x16x32_bf16 v[10:13], v[164:167], v[212:215], v[10:13]
	v_mfma_f32_16x16x32_bf16 v[54:57], v[168:171], v[184:187], v[54:57]
	v_mfma_f32_16x16x32_bf16 v[46:49], v[176:179], v[184:187], v[46:49]
	v_mfma_f32_16x16x32_bf16 v[38:41], v[168:171], v[192:195], v[38:41]
	v_mfma_f32_16x16x32_bf16 v[30:33], v[176:179], v[192:195], v[30:33]
	v_mfma_f32_16x16x32_bf16 v[22:25], v[168:171], v[200:203], v[22:25]
	v_mfma_f32_16x16x32_bf16 v[14:17], v[176:179], v[200:203], v[14:17]
	v_mfma_f32_16x16x32_bf16 v[6:9], v[168:171], v[208:211], v[6:9]
	v_mfma_f32_16x16x32_bf16 v[2:5], v[176:179], v[208:211], v[2:5]
	v_mfma_f32_16x16x32_bf16 v[54:57], v[172:175], v[188:191], v[54:57]
	v_mfma_f32_16x16x32_bf16 v[46:49], v[180:183], v[188:191], v[46:49]
	v_mfma_f32_16x16x32_bf16 v[38:41], v[172:175], v[196:199], v[38:41]
	v_mfma_f32_16x16x32_bf16 v[30:33], v[180:183], v[196:199], v[30:33]
	v_mfma_f32_16x16x32_bf16 v[22:25], v[172:175], v[204:207], v[22:25]
	v_mfma_f32_16x16x32_bf16 v[14:17], v[180:183], v[204:207], v[14:17]
	v_mfma_f32_16x16x32_bf16 v[6:9], v[172:175], v[212:215], v[6:9]
	v_mfma_f32_16x16x32_bf16 v[2:5], v[180:183], v[212:215], v[2:5]
	s_barrier
	s_add_i32 s75, s75, 2
	s_add_u32 s20, s20, 0x100
	s_addc_u32 s21, s21, 0
	s_add_u32 s73, s73, 0x100
	s_addc_u32 s74, s74, 0
	s_cmp_gt_u32 s75, 13
	s_cbranch_scc1 .Lpp0_x

; #define PG8_BAR __builtin_amdgcn_s_barrier()
; template <class Epi, class Sched, bool ALIGN_EPI = false, bool SP2 = false>
; __device__ __forceinline__ void gemm_phase(PG8_LAS unsigned char* lds, const Gemm g, const Sched& S, const Epi& E) {
;     ...
;         if constexpr (ALIGN_EPI) { if (wr == 0) PG8_BAR; }
.Lpp0_x:
	s_and_b64 vcc, exec, s[8:9]
	s_cbranch_vccz .LBB0_195
	s_barrier

; #define PG8_STAGE(bufoff, gbase, voff) do { _Pragma("unroll") for (int _i = 0; _i < 2; ++_i) \
;         __builtin_amdgcn_global_load_lds((const unsigned*)((const char*)(gbase) + (voff)[_i]), (PG8_LAS unsigned*)(lds + (bufoff) + ldsw + _i * 8192), 16, 0, 0); } while (0)
; #define PG8_LDA(dst, b, h) do { _Pragma("unroll") for (int m = 0; m < 4; ++m) _Pragma("unroll") for (int k = 0; k < 2; ++k) dst[m][k] = *(const PG8_LAS bf16x8*)(lds + PG8_SA(b, h) + aoff + m * 2048 + k * 1024); } while (0)
; #define PG8_LDB(dst, b, h) do { _Pragma("unroll") for (int n = 0; n < 2; ++n) _Pragma("unroll") for (int k = 0; k < 2; ++k) dst[n][k] = *(const PG8_LAS bf16x8*)(lds + PG8_SB(b, h) + boff + n * 2048 + k * 1024); } while (0)
; #define PG8_WAIT_V(n) asm volatile("s_waitcnt vmcnt(" #n ")" ::: "memory")
; #define PG8_WAIT_L(n) asm volatile("s_waitcnt lgkmcnt(" #n ")" ::: "memory")
; #define PG8_BAR __builtin_amdgcn_s_barrier()
; #define PG8_SCHED __builtin_amdgcn_sched_barrier(0)
; template <class Epi, class Sched, bool ALIGN_EPI = false, bool SP2 = false>
; __device__ __forceinline__ void gemm_phase(PG8_LAS unsigned char* lds, const Gemm g, const Sched& S, const Epi& E) {
;     ...
;         const bool has_next = S.next(ui + 1, nxt);
;         const char* nA = has_next ? (const char*)g.A + (size_t)nxt.pm * tstep : cA; const char* nB = has_next ? (const char*)g.Bt + (size_t)nxt.pn * tstep : cB;
;         for (int t = 0; t < nt; t += 2) {
;             if constexpr (Epi::HAS_MID) { if (t == nt / 2) E.mid(acc, cur, wr, wc, fr, fq); }
;             const bool last = (t == nt - 2);
;             const char* a1 = cA + (size_t)(t + 1) * kstep;
;             const char* a2 = last ? nA : cA + (size_t)(t + 2) * kstep; const char* b2 = last ? nB : cB + (size_t)(t + 2) * kstep;
;             const char* a3 = a2 + kstep; const char* b3 = b2 + kstep;
;             if (last && has_next) S.a_ready(nxt);
;             if constexpr (SP2) {
;             PG8_LDB(B0, 0, 0); PG8_LDB(B1, 0, 1); PG8_SCHED; PG8_LDA(At, 0, 0); PG8_STAGE(PG8_SA(1, 1), a1 + hstep, voffA);
;             PG8_WAIT_V(8); PG8_WAIT_L(0); PG8_BAR; PG8_MMA(0, 0, At, B0); PG8_MMA(0, 1, At, B1); PG8_BAR; PG8_SCHED;
;             PG8_LDA(At, 0, 1); PG8_STAGE(PG8_SB(0, 0), b2, voffB); PG8_STAGE(PG8_SB(0, 1), b2 + hstepB, voffB); PG8_STAGE(PG8_SA(0, 0), a2, voffA);
.LBB0_1312:
	s_ashr_i32 s27, s26, 31
	s_lshl_b64 s[28:29], s[26:27], 19
	s_add_u32 s28, s12, s28
	s_addc_u32 s29, s13, s29
	s_and_b64 s[34:35], s[6:7], exec
	s_cselect_b32 s9, s29, s39
	s_cselect_b32 s27, s28, s38
	s_ashr_i32 s25, s24, 31
	s_lshl_b64 s[34:35], s[24:25], 19
	s_add_u32 s34, s78, s34
	s_addc_u32 s35, s79, s35
	s_and_b64 s[42:43], s[6:7], exec
	s_cselect_b32 s25, s35, s41
	s_cselect_b32 s37, s34, s40
	s_add_u32 s38, s38, 0x40080
	s_addc_u32 s39, s39, 0
	s_add_u32 s59, s40, 0x100
	s_addc_u32 s60, s41, 0
	s_mov_b32 s61, -2
	ds_read_b128 v[146:149], v154
	ds_read_b128 v[158:161], v154 offset:1024
	ds_read_b128 v[162:165], v154 offset:2048
	ds_read_b128 v[166:169], v154 offset:3072
	ds_read_b128 v[170:173], v155
	ds_read_b128 v[174:177], v155 offset:1024
	ds_read_b128 v[178:181], v155 offset:2048
	ds_read_b128 v[182:185], v155 offset:3072
	s_add_u32 s40, s38, 0xfffc0080
	s_addc_u32 s41, s39, -1
	s_cmp_eq_u32 s61, 12
	s_cselect_b32 s43, s9, s41
	s_cselect_b32 s42, s27, s40
	s_cselect_b32 s41, s25, s60
	s_cselect_b32 s40, s37, s59
	v_lshl_add_u64 v[150:151], s[38:39], 0, v[138:139]
	s_add_i32 m0, s31, 0xc000
	ds_read_b128 v[186:189], v156
	ds_read_b128 v[190:193], v156 offset:1024
	ds_read_b128 v[194:197], v156 offset:2048
	ds_read_b128 v[198:201], v156 offset:3072
	ds_read_b128 v[202:205], v156 offset:4096
	ds_read_b128 v[206:209], v156 offset:5120
	ds_read_b128 v[210:213], v156 offset:6144
	ds_read_b128 v[214:217], v156 offset:7168
	global_load_lds_dwordx4 v[150:151], off
	v_lshl_add_u64 v[150:151], s[38:39], 0, v[140:141]
	s_add_i32 m0, s31, 0xe000
	s_nop 0
	global_load_lds_dwordx4 v[150:151], off
	s_waitcnt vmcnt(8)
	s_waitcnt lgkmcnt(0)
	s_barrier
	v_mfma_f32_16x16x32_bf16 v[126:129], v[146:149], v[186:189], 0
	v_mfma_f32_16x16x32_bf16 v[122:125], v[162:165], v[186:189], 0
	v_mfma_f32_16x16x32_bf16 v[110:113], v[146:149], v[194:197], 0
	v_mfma_f32_16x16x32_bf16 v[106:109], v[162:165], v[194:197], 0
	v_mfma_f32_16x16x32_bf16 v[94:97], v[146:149], v[202:205], 0
	v_mfma_f32_16x16x32_bf16 v[90:93], v[162:165], v[202:205], 0
	v_mfma_f32_16x16x32_bf16 v[78:81], v[146:149], v[210:213], 0
	v_mfma_f32_16x16x32_bf16 v[74:77], v[162:165], v[210:213], 0
	v_mfma_f32_16x16x32_bf16 v[126:129], v[158:161], v[190:193], v[126:129]
	v_mfma_f32_16x16x32_bf16 v[122:125], v[166:169], v[190:193], v[122:125]
	v_mfma_f32_16x16x32_bf16 v[110:113], v[158:161], v[198:201], v[110:113]
	v_mfma_f32_16x16x32_bf16 v[106:109], v[166:169], v[198:201], v[106:109]
	v_mfma_f32_16x16x32_bf16 v[94:97], v[158:161], v[206:209], v[94:97]
	v_mfma_f32_16x16x32_bf16 v[90:93], v[166:169], v[206:209], v[90:93]
	v_mfma_f32_16x16x32_bf16 v[78:81], v[158:161], v[214:217], v[78:81]
	v_mfma_f32_16x16x32_bf16 v[74:77], v[166:169], v[214:217], v[74:77]
	v_mfma_f32_16x16x32_bf16 v[118:121], v[170:173], v[186:189], 0
	v_mfma_f32_16x16x32_bf16 v[114:117], v[178:181], v[186:189], 0
	v_mfma_f32_16x16x32_bf16 v[102:105], v[170:173], v[194:197], 0
	v_mfma_f32_16x16x32_bf16 v[98:101], v[178:181], v[194:197], 0
	v_mfma_f32_16x16x32_bf16 v[86:89], v[170:173], v[202:205], 0
	v_mfma_f32_16x16x32_bf16 v[82:85], v[178:181], v[202:205], 0
	v_mfma_f32_16x16x32_bf16 v[70:73], v[170:173], v[210:213], 0
	v_mfma_f32_16x16x32_bf16 v[66:69], v[178:181], v[210:213], 0
	v_mfma_f32_16x16x32_bf16 v[118:121], v[174:177], v[190:193], v[118:121]
	v_mfma_f32_16x16x32_bf16 v[114:117], v[182:185], v[190:193], v[114:117]
	v_mfma_f32_16x16x32_bf16 v[102:105], v[174:177], v[198:201], v[102:105]
	v_mfma_f32_16x16x32_bf16 v[98:101], v[182:185], v[198:201], v[98:101]
	v_mfma_f32_16x16x32_bf16 v[86:89], v[174:177], v[206:209], v[86:89]
	v_mfma_f32_16x16x32_bf16 v[82:85], v[182:185], v[206:209], v[82:85]
	v_mfma_f32_16x16x32_bf16 v[70:73], v[174:177], v[214:217], v[70:73]
	v_mfma_f32_16x16x32_bf16 v[66:69], v[182:185], v[214:217], v[66:69]
	s_barrier
	s_add_i32 s62, s57, s30
	v_lshl_add_u64 v[150:151], s[40:41], 0, v[132:133]
	s_mov_b32 m0, s62
	ds_read_b128 v[186:189], v156 offset:16384
	ds_read_b128 v[190:193], v156 offset:17408
	ds_read_b128 v[194:197], v156 offset:18432
	ds_read_b128 v[198:201], v156 offset:19456
	ds_read_b128 v[202:205], v156 offset:20480
	ds_read_b128 v[206:209], v156 offset:21504
	ds_read_b128 v[210:213], v156 offset:22528
	ds_read_b128 v[214:217], v156 offset:23552
	global_load_lds_dwordx4 v[150:151], off
	s_add_i32 m0, s62, 0x2000
	s_add_u32 s62, s40, 0x10000
	v_lshl_add_u64 v[218:219], s[40:41], 0, v[136:137]
	s_addc_u32 s63, s41, 0
	s_add_i32 s64, s58, s30
	global_load_lds_dwordx4 v[218:219], off
	v_lshl_add_u64 v[220:221], s[62:63], 0, v[132:133]
	s_mov_b32 m0, s64
	v_lshl_add_u64 v[222:223], s[42:43], 0, v[134:135]
	global_load_lds_dwordx4 v[220:221], off
	v_lshl_add_u64 v[220:221], s[62:63], 0, v[136:137]
	s_add_i32 m0, s64, 0x2000
	s_nop 0
	global_load_lds_dwordx4 v[220:221], off
	v_lshl_add_u64 v[220:221], s[42:43], 0, v[130:131]
	s_mov_b32 m0, s31
	s_nop 0
	global_load_lds_dwordx4 v[220:221], off
	s_mov_b32 m0, s33
	s_nop 0
	global_load_lds_dwordx4 v[222:223], off
	s_waitcnt vmcnt(8)
	s_waitcnt lgkmcnt(0)
	s_barrier
; #define PG8_STAGE(bufoff, gbase, voff) do { _Pragma("unroll") for (int _i = 0; _i < 2; ++_i) \
;         __builtin_amdgcn_global_load_lds((const unsigned*)((const char*)(gbase) + (voff)[_i]), (PG8_LAS unsigned*)(lds + (bufoff) + ldsw + _i * 8192), 16, 0, 0); } while (0)
; #define PG8_LDA(dst, b, h) do { _Pragma("unroll") for (int m = 0; m < 4; ++m) _Pragma("unroll") for (int k = 0; k < 2; ++k) dst[m][k] = *(const PG8_LAS bf16x8*)(lds + PG8_SA(b, h) + aoff + m * 2048 + k * 1024); } while (0)
; #define PG8_LDB(dst, b, h) do { _Pragma("unroll") for (int n = 0; n < 2; ++n) _Pragma("unroll") for (int k = 0; k < 2; ++k) dst[n][k] = *(const PG8_LAS bf16x8*)(lds + PG8_SB(b, h) + boff + n * 2048 + k * 1024); } while (0)
; #define PG8_MMA(ai, bj, At, Bt) do { __builtin_amdgcn_s_setprio(1); _Pragma("unroll") for (int m = 0; m < 4; ++m) _Pragma("unroll") for (int n = 0; n < 2; ++n) _Pragma("unroll") for (int k = 0; k < 2; ++k) \
;         acc[ai][bj][m][n] = __builtin_amdgcn_mfma_f32_16x16x32_bf16(Bt[n][k], At[m][k], acc[ai][bj][m][n], 0, 0, 0); __builtin_amdgcn_s_setprio(0); } while (0)
; #define PG8_WAIT_V(n) asm volatile("s_waitcnt vmcnt(" #n ")" ::: "memory")
; #define PG8_WAIT_L(n) asm volatile("s_waitcnt lgkmcnt(" #n ")" ::: "memory")
; #define PG8_BAR __builtin_amdgcn_s_barrier()
; #define PG8_SCHED __builtin_amdgcn_sched_barrier(0)
; template <class Epi, class Sched, bool ALIGN_EPI = false, bool SP2 = false>
; __device__ __forceinline__ void gemm_phase(PG8_LAS unsigned char* lds, const Gemm g, const Sched& S, const Epi& E) {
;     ...
;             PG8_WAIT_V(8); PG8_WAIT_L(0); PG8_BAR; PG8_MMA(1, 0, At, B0); PG8_MMA(1, 1, At, B1); PG8_BAR; PG8_SCHED;
;             PG8_LDB(B0, 1, 0); PG8_LDB(B1, 1, 1); PG8_SCHED; PG8_LDA(At, 1, 0); PG8_STAGE(PG8_SA(0, 1), a2 + hstep, voffA);
;             PG8_WAIT_V(8); PG8_WAIT_L(0); PG8_BAR; PG8_MMA(0, 0, At, B0); PG8_MMA(0, 1, At, B1); PG8_BAR; PG8_SCHED;
	v_mfma_f32_16x16x32_bf16 v[62:65], v[146:149], v[186:189], 0
	v_mfma_f32_16x16x32_bf16 v[58:61], v[162:165], v[186:189], 0
	v_mfma_f32_16x16x32_bf16 v[46:49], v[146:149], v[194:197], 0
	v_mfma_f32_16x16x32_bf16 v[42:45], v[162:165], v[194:197], 0
	v_mfma_f32_16x16x32_bf16 v[30:33], v[146:149], v[202:205], 0
	v_mfma_f32_16x16x32_bf16 v[26:29], v[162:165], v[202:205], 0
	v_mfma_f32_16x16x32_bf16 v[14:17], v[146:149], v[210:213], 0
	v_mfma_f32_16x16x32_bf16 v[10:13], v[162:165], v[210:213], 0
	v_mfma_f32_16x16x32_bf16 v[62:65], v[158:161], v[190:193], v[62:65]
	v_mfma_f32_16x16x32_bf16 v[58:61], v[166:169], v[190:193], v[58:61]
	v_mfma_f32_16x16x32_bf16 v[46:49], v[158:161], v[198:201], v[46:49]
	v_mfma_f32_16x16x32_bf16 v[42:45], v[166:169], v[198:201], v[42:45]
	v_mfma_f32_16x16x32_bf16 v[30:33], v[158:161], v[206:209], v[30:33]
	v_mfma_f32_16x16x32_bf16 v[26:29], v[166:169], v[206:209], v[26:29]
	v_mfma_f32_16x16x32_bf16 v[14:17], v[158:161], v[214:217], v[14:17]
	v_mfma_f32_16x16x32_bf16 v[10:13], v[166:169], v[214:217], v[10:13]
	v_mfma_f32_16x16x32_bf16 v[54:57], v[170:173], v[186:189], 0
	v_mfma_f32_16x16x32_bf16 v[50:53], v[178:181], v[186:189], 0
	v_mfma_f32_16x16x32_bf16 v[38:41], v[170:173], v[194:197], 0
	v_mfma_f32_16x16x32_bf16 v[34:37], v[178:181], v[194:197], 0
	v_mfma_f32_16x16x32_bf16 v[22:25], v[170:173], v[202:205], 0
	v_mfma_f32_16x16x32_bf16 v[18:21], v[178:181], v[202:205], 0
	v_mfma_f32_16x16x32_bf16 v[6:9], v[170:173], v[210:213], 0
	v_mfma_f32_16x16x32_bf16 v[2:5], v[178:181], v[210:213], 0
	v_mfma_f32_16x16x32_bf16 v[54:57], v[174:177], v[190:193], v[54:57]
	v_mfma_f32_16x16x32_bf16 v[50:53], v[182:185], v[190:193], v[50:53]
	v_mfma_f32_16x16x32_bf16 v[38:41], v[174:177], v[198:201], v[38:41]
	v_mfma_f32_16x16x32_bf16 v[34:37], v[182:185], v[198:201], v[34:37]
	v_mfma_f32_16x16x32_bf16 v[22:25], v[174:177], v[206:209], v[22:25]
	v_mfma_f32_16x16x32_bf16 v[18:21], v[182:185], v[206:209], v[18:21]
	v_mfma_f32_16x16x32_bf16 v[6:9], v[174:177], v[214:217], v[6:9]
	v_mfma_f32_16x16x32_bf16 v[2:5], v[182:185], v[214:217], v[2:5]
	s_barrier
	s_add_i32 s62, 0, 0x18000
	v_add_u32_e32 v157, s62, v152
	s_add_i32 s63, 0, 0x1c000
	ds_read_b128 v[146:149], v157
	ds_read_b128 v[158:161], v157 offset:1024
	ds_read_b128 v[162:165], v157 offset:2048
	ds_read_b128 v[166:169], v157 offset:3072
	v_add_u32_e32 v157, s63, v152
	ds_read_b128 v[170:173], v157
	ds_read_b128 v[174:177], v157 offset:1024
	ds_read_b128 v[178:181], v157 offset:2048
	ds_read_b128 v[182:185], v157 offset:3072
	s_add_u32 s42, s42, 0x40000
	s_addc_u32 s43, s43, 0
	s_mov_b32 m0, s44
	v_lshl_add_u64 v[224:225], s[42:43], 0, v[130:131]
	ds_read_b128 v[186:189], v156 offset:32768
	ds_read_b128 v[190:193], v156 offset:33792
	ds_read_b128 v[194:197], v156 offset:34816
	ds_read_b128 v[198:201], v156 offset:35840
	ds_read_b128 v[202:205], v156 offset:36864
	ds_read_b128 v[206:209], v156 offset:37888
	ds_read_b128 v[210:213], v156 offset:38912
	ds_read_b128 v[214:217], v156 offset:39936
	global_load_lds_dwordx4 v[224:225], off
	v_lshl_add_u64 v[224:225], s[42:43], 0, v[134:135]
	s_mov_b32 m0, s45
	s_nop 0
	global_load_lds_dwordx4 v[224:225], off
	s_waitcnt vmcnt(8)
	s_waitcnt lgkmcnt(0)
	s_barrier
	v_mfma_f32_16x16x32_bf16 v[126:129], v[146:149], v[186:189], v[126:129]
	v_mfma_f32_16x16x32_bf16 v[122:125], v[162:165], v[186:189], v[122:125]
	v_mfma_f32_16x16x32_bf16 v[110:113], v[146:149], v[194:197], v[110:113]
	v_mfma_f32_16x16x32_bf16 v[106:109], v[162:165], v[194:197], v[106:109]
	v_mfma_f32_16x16x32_bf16 v[94:97], v[146:149], v[202:205], v[94:97]
	v_mfma_f32_16x16x32_bf16 v[90:93], v[162:165], v[202:205], v[90:93]
	v_mfma_f32_16x16x32_bf16 v[78:81], v[146:149], v[210:213], v[78:81]
	v_mfma_f32_16x16x32_bf16 v[74:77], v[162:165], v[210:213], v[74:77]
	v_mfma_f32_16x16x32_bf16 v[126:129], v[158:161], v[190:193], v[126:129]
	v_mfma_f32_16x16x32_bf16 v[122:125], v[166:169], v[190:193], v[122:125]
	v_mfma_f32_16x16x32_bf16 v[110:113], v[158:161], v[198:201], v[110:113]
	v_mfma_f32_16x16x32_bf16 v[106:109], v[166:169], v[198:201], v[106:109]
	v_mfma_f32_16x16x32_bf16 v[94:97], v[158:161], v[206:209], v[94:97]
	v_mfma_f32_16x16x32_bf16 v[90:93], v[166:169], v[206:209], v[90:93]
	v_mfma_f32_16x16x32_bf16 v[78:81], v[158:161], v[214:217], v[78:81]
	v_mfma_f32_16x16x32_bf16 v[74:77], v[166:169], v[214:217], v[74:77]
	v_mfma_f32_16x16x32_bf16 v[118:121], v[170:173], v[186:189], v[118:121]
	v_mfma_f32_16x16x32_bf16 v[114:117], v[178:181], v[186:189], v[114:117]
	v_mfma_f32_16x16x32_bf16 v[102:105], v[170:173], v[194:197], v[102:105]
	v_mfma_f32_16x16x32_bf16 v[98:101], v[178:181], v[194:197], v[98:101]
	v_mfma_f32_16x16x32_bf16 v[86:89], v[170:173], v[202:205], v[86:89]
	v_mfma_f32_16x16x32_bf16 v[82:85], v[178:181], v[202:205], v[82:85]
	v_mfma_f32_16x16x32_bf16 v[70:73], v[170:173], v[210:213], v[70:73]
	v_mfma_f32_16x16x32_bf16 v[66:69], v[178:181], v[210:213], v[66:69]
	v_mfma_f32_16x16x32_bf16 v[118:121], v[174:177], v[190:193], v[118:121]
	v_mfma_f32_16x16x32_bf16 v[114:117], v[182:185], v[190:193], v[114:117]
	v_mfma_f32_16x16x32_bf16 v[102:105], v[174:177], v[198:201], v[102:105]
	v_mfma_f32_16x16x32_bf16 v[98:101], v[182:185], v[198:201], v[98:101]
	v_mfma_f32_16x16x32_bf16 v[86:89], v[174:177], v[206:209], v[86:89]
	v_mfma_f32_16x16x32_bf16 v[82:85], v[182:185], v[206:209], v[82:85]
	v_mfma_f32_16x16x32_bf16 v[70:73], v[174:177], v[214:217], v[70:73]
	v_mfma_f32_16x16x32_bf16 v[66:69], v[182:185], v[214:217], v[66:69]
	s_barrier
; #define PG8_STAGE(bufoff, gbase, voff) do { _Pragma("unroll") for (int _i = 0; _i < 2; ++_i) \
;         __builtin_amdgcn_global_load_lds((const unsigned*)((const char*)(gbase) + (voff)[_i]), (PG8_LAS unsigned*)(lds + (bufoff) + ldsw + _i * 8192), 16, 0, 0); } while (0)
; #define PG8_LDA(dst, b, h) do { _Pragma("unroll") for (int m = 0; m < 4; ++m) _Pragma("unroll") for (int k = 0; k < 2; ++k) dst[m][k] = *(const PG8_LAS bf16x8*)(lds + PG8_SA(b, h) + aoff + m * 2048 + k * 1024); } while (0)
; #define PG8_MMA(ai, bj, At, Bt) do { __builtin_amdgcn_s_setprio(1); _Pragma("unroll") for (int m = 0; m < 4; ++m) _Pragma("unroll") for (int n = 0; n < 2; ++n) _Pragma("unroll") for (int k = 0; k < 2; ++k) \
;         acc[ai][bj][m][n] = __builtin_amdgcn_mfma_f32_16x16x32_bf16(Bt[n][k], At[m][k], acc[ai][bj][m][n], 0, 0, 0); __builtin_amdgcn_s_setprio(0); } while (0)
; #define PG8_WAIT_V(n) asm volatile("s_waitcnt vmcnt(" #n ")" ::: "memory")
; #define PG8_WAIT_L(n) asm volatile("s_waitcnt lgkmcnt(" #n ")" ::: "memory")
; #define PG8_BAR __builtin_amdgcn_s_barrier()
; #define PG8_SCHED __builtin_amdgcn_sched_barrier(0)
; template <class Epi, class Sched, bool ALIGN_EPI = false, bool SP2 = false>
; __device__ __forceinline__ void gemm_phase(PG8_LAS unsigned char* lds, const Gemm g, const Sched& S, const Epi& E) {
;     ...
;         for (int t = 0; t < nt; t += 2) {
;     ...
;             PG8_LDA(At, 1, 1); PG8_STAGE(PG8_SB(1, 0), b3, voffB); PG8_STAGE(PG8_SB(1, 1), b3 + hstepB, voffB); PG8_STAGE(PG8_SA(1, 0), a3, voffA);
;             PG8_WAIT_V(8); PG8_WAIT_L(0); PG8_BAR; PG8_MMA(1, 0, At, B0); PG8_MMA(1, 1, At, B1); PG8_BAR; PG8_SCHED;
	s_add_i32 s42, s62, s30
	v_lshl_add_u64 v[150:151], v[150:151], 0, s[10:11]
	s_mov_b32 m0, s42
	ds_read_b128 v[186:189], v156 offset:49152
	ds_read_b128 v[190:193], v156 offset:50176
	ds_read_b128 v[194:197], v156 offset:51200
	ds_read_b128 v[198:201], v156 offset:52224
	ds_read_b128 v[202:205], v156 offset:53248
	ds_read_b128 v[206:209], v156 offset:54272
	ds_read_b128 v[210:213], v156 offset:55296
	ds_read_b128 v[214:217], v156 offset:56320
	global_load_lds_dwordx4 v[150:151], off
	s_add_i32 m0, s42, 0x2000
	s_add_u32 s40, s40, 0x10080
	v_lshl_add_u64 v[150:151], v[218:219], 0, s[10:11]
	s_addc_u32 s41, s41, 0
	s_add_i32 s42, s63, s30
	global_load_lds_dwordx4 v[150:151], off
	v_lshl_add_u64 v[150:151], s[40:41], 0, v[132:133]
	s_mov_b32 m0, s42
	s_nop 0
	global_load_lds_dwordx4 v[150:151], off
	v_lshl_add_u64 v[150:151], s[40:41], 0, v[136:137]
	s_add_i32 m0, s42, 0x2000
	s_nop 0
	global_load_lds_dwordx4 v[150:151], off
	v_lshl_add_u64 v[150:151], v[220:221], 0, s[10:11]
	s_mov_b32 m0, s47
	s_nop 0
	global_load_lds_dwordx4 v[150:151], off
	v_lshl_add_u64 v[150:151], v[222:223], 0, s[10:11]
	s_mov_b32 m0, s54
	s_nop 0
	global_load_lds_dwordx4 v[150:151], off
	s_waitcnt vmcnt(8)
	s_waitcnt lgkmcnt(0)
	s_barrier
	v_mfma_f32_16x16x32_bf16 v[62:65], v[146:149], v[186:189], v[62:65]
	v_mfma_f32_16x16x32_bf16 v[58:61], v[162:165], v[186:189], v[58:61]
	v_mfma_f32_16x16x32_bf16 v[46:49], v[146:149], v[194:197], v[46:49]
	v_mfma_f32_16x16x32_bf16 v[42:45], v[162:165], v[194:197], v[42:45]
	v_mfma_f32_16x16x32_bf16 v[30:33], v[146:149], v[202:205], v[30:33]
	v_mfma_f32_16x16x32_bf16 v[26:29], v[162:165], v[202:205], v[26:29]
	v_mfma_f32_16x16x32_bf16 v[14:17], v[146:149], v[210:213], v[14:17]
	v_mfma_f32_16x16x32_bf16 v[10:13], v[162:165], v[210:213], v[10:13]
	v_mfma_f32_16x16x32_bf16 v[62:65], v[158:161], v[190:193], v[62:65]
	v_mfma_f32_16x16x32_bf16 v[58:61], v[166:169], v[190:193], v[58:61]
	v_mfma_f32_16x16x32_bf16 v[46:49], v[158:161], v[198:201], v[46:49]
	v_mfma_f32_16x16x32_bf16 v[42:45], v[166:169], v[198:201], v[42:45]
	v_mfma_f32_16x16x32_bf16 v[30:33], v[158:161], v[206:209], v[30:33]
	v_mfma_f32_16x16x32_bf16 v[26:29], v[166:169], v[206:209], v[26:29]
	v_mfma_f32_16x16x32_bf16 v[14:17], v[158:161], v[214:217], v[14:17]
	v_mfma_f32_16x16x32_bf16 v[10:13], v[166:169], v[214:217], v[10:13]
	v_mfma_f32_16x16x32_bf16 v[54:57], v[170:173], v[186:189], v[54:57]
	v_mfma_f32_16x16x32_bf16 v[50:53], v[178:181], v[186:189], v[50:53]
	v_mfma_f32_16x16x32_bf16 v[38:41], v[170:173], v[194:197], v[38:41]
	v_mfma_f32_16x16x32_bf16 v[34:37], v[178:181], v[194:197], v[34:37]
	v_mfma_f32_16x16x32_bf16 v[22:25], v[170:173], v[202:205], v[22:25]
	v_mfma_f32_16x16x32_bf16 v[18:21], v[178:181], v[202:205], v[18:21]
	v_mfma_f32_16x16x32_bf16 v[6:9], v[170:173], v[210:213], v[6:9]
	v_mfma_f32_16x16x32_bf16 v[2:5], v[178:181], v[210:213], v[2:5]
	v_mfma_f32_16x16x32_bf16 v[54:57], v[174:177], v[190:193], v[54:57]
	v_mfma_f32_16x16x32_bf16 v[50:53], v[182:185], v[190:193], v[50:53]
	v_mfma_f32_16x16x32_bf16 v[38:41], v[174:177], v[198:201], v[38:41]
	v_mfma_f32_16x16x32_bf16 v[34:37], v[182:185], v[198:201], v[34:37]
	v_mfma_f32_16x16x32_bf16 v[22:25], v[174:177], v[206:209], v[22:25]
	v_mfma_f32_16x16x32_bf16 v[18:21], v[182:185], v[206:209], v[18:21]
	v_mfma_f32_16x16x32_bf16 v[6:9], v[174:177], v[214:217], v[6:9]
	v_mfma_f32_16x16x32_bf16 v[2:5], v[182:185], v[214:217], v[2:5]
	s_barrier
	s_add_i32 s61, s61, 2
	s_add_u32 s38, s38, 0x100
	s_addc_u32 s39, s39, 0
	s_add_u32 s59, s59, 0x100
	s_addc_u32 s60, s60, 0
	s_cmp_gt_u32 s61, 13
	s_cbranch_scc1 .Lpp1_x

; #define PG8_BAR __builtin_amdgcn_s_barrier()
; template <class Epi, class Sched, bool ALIGN_EPI = false, bool SP2 = false>
; __device__ __forceinline__ void gemm_phase(PG8_LAS unsigned char* lds, const Gemm g, const Sched& S, const Epi& E) {
;     ...
;         if constexpr (ALIGN_EPI) { if (wr == 0) PG8_BAR; }
.Lpp1_x:
	s_and_b64 vcc, exec, s[14:15]
	s_cbranch_vccz .LBB0_1316
	s_barrier
